# attention phase: one static s_setprio 1 for waves 4-7 (younger half), reset at the SGU/pool phase; on top of the E1+saddr GEMM trims
# baseline (speedup 1.0000x reference)
.LBB0_465:
	s_cmpk_eq_i32 s0, 0x100
	s_cselect_b64 s[16:17], -1, 0
	s_and_b64 s[8:9], s[16:17], exec
	s_movk_i32 s8, 0x120
	s_cselect_b32 s11, 0x200, s8
	v_readlane_b32 s8, v254, 28
	v_readlane_b32 s9, v254, 29
	s_and_b64 s[8:9], s[8:9], exec
	s_cselect_b32 s8, s11, 0x100
	s_cmp_ge_i32 s1, s8
	s_cbranch_scc1 .LBB0_505
	v_readlane_b32 s12, v254, 24
	s_lshl_b32 s22, s12, 3
	s_ashr_i32 s9, s10, 6
	s_waitcnt lgkmcnt(0)
	s_add_u32 s18, s6, 0x1c800000
	s_addc_u32 s19, s7, 0
	s_add_u32 s14, s6, 0x1fe00000
	s_addc_u32 s15, s7, 0
	s_lshl_b64 s[6:7], s[22:23], 2
	s_add_u32 s20, s2, s6
	s_addc_u32 s21, s3, s7
	s_lshl_b32 s2, s9, 5
	s_ashr_i32 s22, s10, 8
	s_and_b32 s28, s2, 0x60
	v_readlane_b32 s13, v254, 25
	s_cmp_lt_u32 s9, 4
	s_cbranch_scc1 .Lattn_prio_done
	s_setprio 1
.Lattn_prio_done:
	s_branch .LBB0_469

.LBB0_505:
	s_setprio 0
	v_readlane_b32 s0, v254, 28
	v_readlane_b32 s1, v254, 29
	s_and_b64 s[0:1], s[0:1], exec
	s_mov_b64 s[16:17], s[94:95]
	v_readlane_b32 s11, v254, 0
	v_mov_b32_e32 v5, v0
	s_mov_b32 s0, s11
	v_readlane_b32 s8, v254, 3
	s_waitcnt lgkmcnt(0)
	s_load_dwordx2 s[2:3], s[16:17], 0x70
	s_load_dwordx2 s[6:7], s[16:17], 0xa0
	s_movk_i32 s0, 0x120
	v_readlane_b32 s12, v254, 24
	s_cselect_b32 s1, s0, 0x100
	s_lshl_b32 s0, s12, 16
	s_lshl_b32 s22, s12, 9
	s_waitcnt lgkmcnt(0)
	s_add_u32 s18, s6, 0x1c800000
	s_addc_u32 s19, s7, 0
	s_add_u32 s26, s6, 0x1fe00000
	s_addc_u32 s27, s7, 0
	s_lshl_b32 s12, s12, 17
	s_mov_b32 s10, s12
	v_readlane_b32 s13, v254, 25
	v_readfirstlane_b32 s9, v5
	v_writelane_b32 v254, s10, 30
	s_add_u32 s6, s6, s12
	s_addc_u32 s7, s7, 0
	v_writelane_b32 v254, s11, 31
	s_ashr_i32 s10, s9, 8
	s_lshl_b64 s[12:13], s[22:23], 2
	s_add_u32 s30, s2, s12
	s_addc_u32 s31, s3, s13
	s_ashr_i32 s2, s9, 1
	s_and_b32 s3, s2, 0xfffff80
	v_lshlrev_b32_e32 v2, 6, v5
	s_and_b32 s2, s2, 0x60
	s_mulk_i32 s3, 0x110
	v_lshrrev_b32_e32 v4, 1, v5
	v_bfe_u32 v87, v5, 1, 7
	v_and_b32_e32 v86, 64, v2
	v_and_or_b32 v97, v5, 15, s2
	s_add_i32 s9, s3, 0
	v_lshlrev_b32_e32 v2, 1, v87
	v_mul_u32_u24_e32 v3, 0x110, v86
	v_lshlrev_b32_e32 v202, 8, v97
	v_and_b32_e32 v4, 24, v4
	v_add3_u32 v93, s9, v2, v3
	v_lshl_add_u64 v[2:3], s[6:7], 0, v[202:203]
	v_lshlrev_b32_e32 v202, 1, v4
	v_lshl_add_u64 v[2:3], v[2:3], 0, v[202:203]
	s_mov_b64 s[2:3], 0x2c590000
	v_lshl_add_u64 v[88:89], v[2:3], 0, s[2:3]
	v_lshlrev_b32_e32 v2, 1, v5
	v_and_b32_e32 v3, 3, v5
	s_mul_i32 s10, s8, s10
	v_and_or_b32 v2, v2, 24, v3
	v_add_u32_e32 v3, s9, v202
	v_mul_u32_u24_e32 v2, 0x110, v2
	s_add_i32 s3, s11, s10
	v_or_b32_e32 v98, 16, v97
	s_lshl_b32 s2, s8, 1
	s_lshl_b32 s6, s3, 5
	s_lshl_b32 s7, s8, 6
	s_mov_b32 s8, 0
	v_lshlrev_b32_e32 v90, 1, v4
	v_add_u32_e32 v99, v3, v2
	s_branch .LBB0_507
